# adds: P5 SwiGLU epilogue hand-rewritten (packed adds, scalar row addressing, same per-element operations, bit-identical)
# speedup vs baseline: 1.0010x; 1.0010x over previous
.LBB0_771:
	v_mul_u32_u24_e32 v246, 0x1600, v150
	s_mul_i32 s82, s36, 0x160000
	s_lshl_b32 s83, s28, 8
	v_mov_b32_e32 v240, 1.0
	s_add_u32 s86, s8, s82
	s_addc_u32 s87, s9, 0
	v_mov_b32_e32 v241, 1.0
	s_add_u32 s86, s86, s83
	s_addc_u32 s87, s87, 0
	v_lshl_add_u32 v246, v152, 1, v246
	v_exp_f32_e64 v232, -v126
	v_exp_f32_e64 v233, -v127
	v_exp_f32_e64 v234, -v128
	v_exp_f32_e64 v235, -v129
	v_exp_f32_e64 v236, -v122
	v_exp_f32_e64 v237, -v123
	v_exp_f32_e64 v238, -v124
	v_exp_f32_e64 v239, -v125
	v_pk_add_f32 v[232:233], v[232:233], v[240:241]
	v_pk_add_f32 v[234:235], v[234:235], v[240:241]
	v_pk_add_f32 v[236:237], v[236:237], v[240:241]
	v_pk_add_f32 v[238:239], v[238:239], v[240:241]
	v_rcp_f32_e32 v232, v232
	v_rcp_f32_e32 v233, v233
	v_rcp_f32_e32 v234, v234
	v_rcp_f32_e32 v235, v235
	v_rcp_f32_e32 v236, v236
	v_rcp_f32_e32 v237, v237
	v_rcp_f32_e32 v238, v238
	v_rcp_f32_e32 v239, v239
	v_pk_mul_f32 v[118:119], v[126:127], v[118:119]
	v_pk_mul_f32 v[120:121], v[128:129], v[120:121]
	v_pk_mul_f32 v[114:115], v[122:123], v[114:115]
	v_pk_mul_f32 v[116:117], v[124:125], v[116:117]
	v_pk_mul_f32 v[118:119], v[232:233], v[118:119]
	v_pk_mul_f32 v[120:121], v[234:235], v[120:121]
	v_pk_mul_f32 v[114:115], v[236:237], v[114:115]
	v_pk_mul_f32 v[116:117], v[238:239], v[116:117]
	v_cvt_pk_bf16_f32 v242, v118, v119
	v_cvt_pk_bf16_f32 v243, v120, v121
	v_cvt_pk_bf16_f32 v244, v114, v115
	v_cvt_pk_bf16_f32 v245, v116, v117
	s_add_u32 s84, s86, 0x0
	s_addc_u32 s85, s87, 0
	global_store_dwordx4 v246, v[242:245], s[84:85] sc1
	s_nop 1
	v_exp_f32_e64 v232, -v110
	v_exp_f32_e64 v233, -v111
	v_exp_f32_e64 v234, -v112
	v_exp_f32_e64 v235, -v113
	v_exp_f32_e64 v236, -v106
	v_exp_f32_e64 v237, -v107
	v_exp_f32_e64 v238, -v108
	v_exp_f32_e64 v239, -v109
	v_pk_add_f32 v[232:233], v[232:233], v[240:241]
	v_pk_add_f32 v[234:235], v[234:235], v[240:241]
	v_pk_add_f32 v[236:237], v[236:237], v[240:241]
	v_pk_add_f32 v[238:239], v[238:239], v[240:241]
	v_rcp_f32_e32 v232, v232
	v_rcp_f32_e32 v233, v233
	v_rcp_f32_e32 v234, v234
	v_rcp_f32_e32 v235, v235
	v_rcp_f32_e32 v236, v236
	v_rcp_f32_e32 v237, v237
	v_rcp_f32_e32 v238, v238
	v_rcp_f32_e32 v239, v239
	v_pk_mul_f32 v[102:103], v[110:111], v[102:103]
	v_pk_mul_f32 v[104:105], v[112:113], v[104:105]
	v_pk_mul_f32 v[98:99], v[106:107], v[98:99]
	v_pk_mul_f32 v[100:101], v[108:109], v[100:101]
	v_pk_mul_f32 v[102:103], v[232:233], v[102:103]
	v_pk_mul_f32 v[104:105], v[234:235], v[104:105]
	v_pk_mul_f32 v[98:99], v[236:237], v[98:99]
	v_pk_mul_f32 v[100:101], v[238:239], v[100:101]
	v_cvt_pk_bf16_f32 v242, v102, v103
	v_cvt_pk_bf16_f32 v243, v104, v105
	v_cvt_pk_bf16_f32 v244, v98, v99
	v_cvt_pk_bf16_f32 v245, v100, v101
	s_add_u32 s84, s86, 0x16000
	s_addc_u32 s85, s87, 0
	global_store_dwordx4 v246, v[242:245], s[84:85] sc1
	s_nop 1
	v_exp_f32_e64 v232, -v94
	v_exp_f32_e64 v233, -v95
	v_exp_f32_e64 v234, -v96
	v_exp_f32_e64 v235, -v97
	v_exp_f32_e64 v236, -v90
	v_exp_f32_e64 v237, -v91
	v_exp_f32_e64 v238, -v92
	v_exp_f32_e64 v239, -v93
	v_pk_add_f32 v[232:233], v[232:233], v[240:241]
	v_pk_add_f32 v[234:235], v[234:235], v[240:241]
	v_pk_add_f32 v[236:237], v[236:237], v[240:241]
	v_pk_add_f32 v[238:239], v[238:239], v[240:241]
	v_rcp_f32_e32 v232, v232
	v_rcp_f32_e32 v233, v233
	v_rcp_f32_e32 v234, v234
	v_rcp_f32_e32 v235, v235
	v_rcp_f32_e32 v236, v236
	v_rcp_f32_e32 v237, v237
	v_rcp_f32_e32 v238, v238
	v_rcp_f32_e32 v239, v239
	v_pk_mul_f32 v[86:87], v[94:95], v[86:87]
	v_pk_mul_f32 v[88:89], v[96:97], v[88:89]
	v_pk_mul_f32 v[82:83], v[90:91], v[82:83]
	v_pk_mul_f32 v[84:85], v[92:93], v[84:85]
	v_pk_mul_f32 v[86:87], v[232:233], v[86:87]
	v_pk_mul_f32 v[88:89], v[234:235], v[88:89]
	v_pk_mul_f32 v[82:83], v[236:237], v[82:83]
	v_pk_mul_f32 v[84:85], v[238:239], v[84:85]
	v_cvt_pk_bf16_f32 v242, v86, v87
	v_cvt_pk_bf16_f32 v243, v88, v89
	v_cvt_pk_bf16_f32 v244, v82, v83
	v_cvt_pk_bf16_f32 v245, v84, v85
	s_add_u32 s84, s86, 0x2c000
	s_addc_u32 s85, s87, 0
	global_store_dwordx4 v246, v[242:245], s[84:85] sc1
	s_nop 1
	v_exp_f32_e64 v232, -v78
	v_exp_f32_e64 v233, -v79
	v_exp_f32_e64 v234, -v80
	v_exp_f32_e64 v235, -v81
	v_exp_f32_e64 v236, -v74
	v_exp_f32_e64 v237, -v75
	v_exp_f32_e64 v238, -v76
	v_exp_f32_e64 v239, -v77
	v_pk_add_f32 v[232:233], v[232:233], v[240:241]
	v_pk_add_f32 v[234:235], v[234:235], v[240:241]
	v_pk_add_f32 v[236:237], v[236:237], v[240:241]
	v_pk_add_f32 v[238:239], v[238:239], v[240:241]
	v_rcp_f32_e32 v232, v232
	v_rcp_f32_e32 v233, v233
	v_rcp_f32_e32 v234, v234
	v_rcp_f32_e32 v235, v235
	v_rcp_f32_e32 v236, v236
	v_rcp_f32_e32 v237, v237
	v_rcp_f32_e32 v238, v238
	v_rcp_f32_e32 v239, v239
	v_pk_mul_f32 v[70:71], v[78:79], v[70:71]
	v_pk_mul_f32 v[72:73], v[80:81], v[72:73]
	v_pk_mul_f32 v[66:67], v[74:75], v[66:67]
	v_pk_mul_f32 v[68:69], v[76:77], v[68:69]
	v_pk_mul_f32 v[70:71], v[232:233], v[70:71]
	v_pk_mul_f32 v[72:73], v[234:235], v[72:73]
	v_pk_mul_f32 v[66:67], v[236:237], v[66:67]
	v_pk_mul_f32 v[68:69], v[238:239], v[68:69]
	v_cvt_pk_bf16_f32 v242, v70, v71
	v_cvt_pk_bf16_f32 v243, v72, v73
	v_cvt_pk_bf16_f32 v244, v66, v67
	v_cvt_pk_bf16_f32 v245, v68, v69
	s_add_u32 s84, s86, 0x42000
	s_addc_u32 s85, s87, 0
	global_store_dwordx4 v246, v[242:245], s[84:85] sc1
	s_nop 1
	v_exp_f32_e64 v232, -v62
	v_exp_f32_e64 v233, -v63
	v_exp_f32_e64 v234, -v64
	v_exp_f32_e64 v235, -v65
	v_exp_f32_e64 v236, -v58
	v_exp_f32_e64 v237, -v59
	v_exp_f32_e64 v238, -v60
	v_exp_f32_e64 v239, -v61
	v_pk_add_f32 v[232:233], v[232:233], v[240:241]
	v_pk_add_f32 v[234:235], v[234:235], v[240:241]
	v_pk_add_f32 v[236:237], v[236:237], v[240:241]
	v_pk_add_f32 v[238:239], v[238:239], v[240:241]
	v_rcp_f32_e32 v232, v232
	v_rcp_f32_e32 v233, v233
	v_rcp_f32_e32 v234, v234
	v_rcp_f32_e32 v235, v235
	v_rcp_f32_e32 v236, v236
	v_rcp_f32_e32 v237, v237
	v_rcp_f32_e32 v238, v238
	v_rcp_f32_e32 v239, v239
	v_pk_mul_f32 v[54:55], v[62:63], v[54:55]
	v_pk_mul_f32 v[56:57], v[64:65], v[56:57]
	v_pk_mul_f32 v[50:51], v[58:59], v[50:51]
	v_pk_mul_f32 v[52:53], v[60:61], v[52:53]
	v_pk_mul_f32 v[54:55], v[232:233], v[54:55]
	v_pk_mul_f32 v[56:57], v[234:235], v[56:57]
	v_pk_mul_f32 v[50:51], v[236:237], v[50:51]
	v_pk_mul_f32 v[52:53], v[238:239], v[52:53]
	v_cvt_pk_bf16_f32 v242, v54, v55
	v_cvt_pk_bf16_f32 v243, v56, v57
	v_cvt_pk_bf16_f32 v244, v50, v51
	v_cvt_pk_bf16_f32 v245, v52, v53
	s_add_u32 s84, s86, 0xb0000
	s_addc_u32 s85, s87, 0
	global_store_dwordx4 v246, v[242:245], s[84:85] sc1
	s_nop 1
	v_exp_f32_e64 v232, -v46
	v_exp_f32_e64 v233, -v47
	v_exp_f32_e64 v234, -v48
	v_exp_f32_e64 v235, -v49
	v_exp_f32_e64 v236, -v42
	v_exp_f32_e64 v237, -v43
	v_exp_f32_e64 v238, -v44
	v_exp_f32_e64 v239, -v45
	v_pk_add_f32 v[232:233], v[232:233], v[240:241]
	v_pk_add_f32 v[234:235], v[234:235], v[240:241]
	v_pk_add_f32 v[236:237], v[236:237], v[240:241]
	v_pk_add_f32 v[238:239], v[238:239], v[240:241]
	v_rcp_f32_e32 v232, v232
	v_rcp_f32_e32 v233, v233
	v_rcp_f32_e32 v234, v234
	v_rcp_f32_e32 v235, v235
	v_rcp_f32_e32 v236, v236
	v_rcp_f32_e32 v237, v237
	v_rcp_f32_e32 v238, v238
	v_rcp_f32_e32 v239, v239
	v_pk_mul_f32 v[38:39], v[46:47], v[38:39]
	v_pk_mul_f32 v[40:41], v[48:49], v[40:41]
	v_pk_mul_f32 v[34:35], v[42:43], v[34:35]
	v_pk_mul_f32 v[36:37], v[44:45], v[36:37]
	v_pk_mul_f32 v[38:39], v[232:233], v[38:39]
	v_pk_mul_f32 v[40:41], v[234:235], v[40:41]
	v_pk_mul_f32 v[34:35], v[236:237], v[34:35]
	v_pk_mul_f32 v[36:37], v[238:239], v[36:37]
	v_cvt_pk_bf16_f32 v242, v38, v39
	v_cvt_pk_bf16_f32 v243, v40, v41
	v_cvt_pk_bf16_f32 v244, v34, v35
	v_cvt_pk_bf16_f32 v245, v36, v37
	s_add_u32 s84, s86, 0xc6000
	s_addc_u32 s85, s87, 0
	global_store_dwordx4 v246, v[242:245], s[84:85] sc1
	s_nop 1
	v_exp_f32_e64 v232, -v30
	v_exp_f32_e64 v233, -v31
	v_exp_f32_e64 v234, -v32
	v_exp_f32_e64 v235, -v33
	v_exp_f32_e64 v236, -v26
	v_exp_f32_e64 v237, -v27
	v_exp_f32_e64 v238, -v28
	v_exp_f32_e64 v239, -v29
	v_pk_add_f32 v[232:233], v[232:233], v[240:241]
	v_pk_add_f32 v[234:235], v[234:235], v[240:241]
	v_pk_add_f32 v[236:237], v[236:237], v[240:241]
	v_pk_add_f32 v[238:239], v[238:239], v[240:241]
	v_rcp_f32_e32 v232, v232
	v_rcp_f32_e32 v233, v233
	v_rcp_f32_e32 v234, v234
	v_rcp_f32_e32 v235, v235
	v_rcp_f32_e32 v236, v236
	v_rcp_f32_e32 v237, v237
	v_rcp_f32_e32 v238, v238
	v_rcp_f32_e32 v239, v239
	v_pk_mul_f32 v[22:23], v[30:31], v[22:23]
	v_pk_mul_f32 v[24:25], v[32:33], v[24:25]
	v_pk_mul_f32 v[18:19], v[26:27], v[18:19]
	v_pk_mul_f32 v[20:21], v[28:29], v[20:21]
	v_pk_mul_f32 v[22:23], v[232:233], v[22:23]
	v_pk_mul_f32 v[24:25], v[234:235], v[24:25]
	v_pk_mul_f32 v[18:19], v[236:237], v[18:19]
	v_pk_mul_f32 v[20:21], v[238:239], v[20:21]
	v_cvt_pk_bf16_f32 v242, v22, v23
	v_cvt_pk_bf16_f32 v243, v24, v25
	v_cvt_pk_bf16_f32 v244, v18, v19
	v_cvt_pk_bf16_f32 v245, v20, v21
	s_add_u32 s84, s86, 0xdc000
	s_addc_u32 s85, s87, 0
	global_store_dwordx4 v246, v[242:245], s[84:85] sc1
	s_nop 1
	v_exp_f32_e64 v232, -v14
	v_exp_f32_e64 v233, -v15
	v_exp_f32_e64 v234, -v16
	v_exp_f32_e64 v235, -v17
	v_exp_f32_e64 v236, -v10
	v_exp_f32_e64 v237, -v11
	v_exp_f32_e64 v238, -v12
	v_exp_f32_e64 v239, -v13
	v_pk_add_f32 v[232:233], v[232:233], v[240:241]
	v_pk_add_f32 v[234:235], v[234:235], v[240:241]
	v_pk_add_f32 v[236:237], v[236:237], v[240:241]
	v_pk_add_f32 v[238:239], v[238:239], v[240:241]
	v_rcp_f32_e32 v232, v232
	v_rcp_f32_e32 v233, v233
	v_rcp_f32_e32 v234, v234
	v_rcp_f32_e32 v235, v235
	v_rcp_f32_e32 v236, v236
	v_rcp_f32_e32 v237, v237
	v_rcp_f32_e32 v238, v238
	v_rcp_f32_e32 v239, v239
	v_pk_mul_f32 v[6:7], v[14:15], v[6:7]
	v_pk_mul_f32 v[8:9], v[16:17], v[8:9]
	v_pk_mul_f32 v[2:3], v[10:11], v[2:3]
	v_pk_mul_f32 v[4:5], v[12:13], v[4:5]
	v_pk_mul_f32 v[6:7], v[232:233], v[6:7]
	v_pk_mul_f32 v[8:9], v[234:235], v[8:9]
	v_pk_mul_f32 v[2:3], v[236:237], v[2:3]
	v_pk_mul_f32 v[4:5], v[238:239], v[4:5]
	v_cvt_pk_bf16_f32 v242, v6, v7
	v_cvt_pk_bf16_f32 v243, v8, v9
	v_cvt_pk_bf16_f32 v244, v2, v3
	v_cvt_pk_bf16_f32 v245, v4, v5
	s_add_u32 s84, s86, 0xf2000
	s_addc_u32 s85, s87, 0
	global_store_dwordx4 v246, v[242:245], s[84:85] sc1
	s_nop 1
	s_andn2_b64 vcc, exec, s[6:7]
	s_mov_b64 s[6:7], -1
	s_cbranch_vccnz .LBB0_764
	s_andn2_b64 vcc, exec, s[10:11]
	s_cbranch_vccnz .LBB0_763
	s_barrier
	s_branch .LBB0_763
